# prep_rwkv LoRA loop with prefetched weight loads; MIX two-queue scheduling with partner hold-off; scan global loads two chunks ahead
# speedup vs baseline: 1.1986x; 1.0590x over previous
.LBB0_98:
	s_and_b64 vcc, exec, s[0:1]
	s_cbranch_vccz .LBB0_146
	s_ashr_i32 s71, s70, 31
	s_lshl_b64 s[0:1], s[70:71], 2
	v_readlane_b32 s2, v255, 15
	v_readlane_b32 s3, v255, 16
	s_add_u32 s36, s2, s0
	s_addc_u32 s37, s3, s1
	s_lshl_b32 s26, s70, 7
	s_mul_i32 s28, s70, 0x920000
	s_ashr_i32 s27, s26, 31
	v_readlane_b32 s2, v254, 37
	s_mul_hi_i32 s25, s70, 0x920000
	s_add_u32 s4, s2, s28
	v_readlane_b32 s2, v254, 38
	s_addc_u32 s5, s2, s25
	v_writelane_b32 v255, s4, 38
	v_readlane_b32 s2, v254, 45
	v_readlane_b32 s3, v254, 46
	v_writelane_b32 v255, s5, 39
	v_writelane_b32 v255, s16, 40
	v_writelane_b32 v255, s18, 42
	s_add_u32 s2, s2, s0
	s_addc_u32 s3, s3, s1
	v_writelane_b32 v255, s19, 43
	v_readlane_b32 s4, v252, 49
	s_lshl_b64 s[0:1], s[26:27], 2
	v_readlane_b32 s12, v252, 57
	v_readlane_b32 s13, v252, 58
	s_add_u32 s12, s12, s0
	s_addc_u32 s13, s13, s1
	s_add_u32 s0, s96, s28
	v_readlane_b32 s14, v252, 59
	v_readlane_b32 s18, v252, 63
	v_readlane_b32 s19, v253, 0
	s_addc_u32 s1, s97, s25
	v_readlane_b32 s15, v252, 60
	v_readlane_b32 s16, v252, 61
	v_readlane_b32 s18, v255, 42
	s_add_u32 s14, s0, 0x5f34000
	s_mov_b32 s0, s70
	v_readlane_b32 s8, v252, 53
	v_readlane_b32 s9, v252, 54
	v_readlane_b32 s10, v252, 55
	v_readlane_b32 s11, v252, 56
	v_readlane_b32 s19, v255, 43
	v_readlane_b32 s16, v255, 40
	s_addc_u32 s15, s1, 0
	v_writelane_b32 v255, s0, 44
	s_mov_b64 s[10:11], s[2:3]
	s_mov_b64 s[8:9], s[36:37]
	v_writelane_b32 v255, s1, 45
	v_readlane_b32 s5, v252, 50
	v_readlane_b32 s6, v252, 51
	v_readlane_b32 s7, v252, 52
	v_readlane_b32 s17, v252, 62
	v_readlane_b32 s101, v252, 0
	s_lshr_b32 s98, s101, 8
	s_and_b32 s98, s98, 1
	s_lshl_b32 s99, s98, 2
	s_and_b32 s101, s101, 0xff
	s_lshr_b32 s100, s101, 5
	s_add_i32 s100, s100, 4
	s_lshl_b32 s100, s100, 6
	s_and_b32 s101, s101, 31
	s_add_i32 s100, s100, s101
	s_add_i32 s100, s100, 1
	s_lshl_b32 s100, s100, 2
	s_add_u32 s100, s100, 0x227a6200
	s_add_u32 s100, s96, s100
	s_addc_u32 s101, s97, 0
	s_cmp_eq_u32 s98, 0
	s_cbranch_scc0 .Lq_init_done
	s_or_b32 s99, s99, 2
	v_readlane_b32 s26, v253, 1
	v_readlane_b32 s27, v253, 2
	s_and_saveexec_b64 s[28:29], s[26:27]
	v_mov_b32_e32 v1, 1
	global_atomic_add v131, v1, s[100:101]
	s_or_b64 exec, exec, s[28:29]
.Lq_init_done:
	s_branch .LBB0_102
.LBB0_100:
	s_mov_b64 s[0:1], 0
	v_readlane_b32 s70, v255, 44
	v_readlane_b32 s71, v255, 45

.LBB0_102:
	v_readlane_b32 s2, v253, 1
	v_readlane_b32 s3, v253, 2
	s_barrier
	s_and_saveexec_b64 s[0:1], s[2:3]
	s_cbranch_execz .Lq_sync
	s_bitcmp1_b32 s99, 2
	s_cbranch_scc0 .Lq_fetch
	s_cmp_eq_u32 s98, 1
	s_cbranch_scc0 .Lq_fetch
	s_movk_i32 s25, 1000
.Lq_spin1:
	global_load_dword v1, v131, s[8:9] sc1
	s_waitcnt vmcnt(0)
	v_cmp_gt_u32_e32 vcc, 0x80, v1
	s_cbranch_vccz .Lq_spin2
	s_sleep 2
	s_add_i32 s25, s25, -1
	s_cmp_gt_i32 s25, 0
	s_cbranch_scc1 .Lq_spin1
.Lq_spin2:
	global_load_dword v1, v131, s[100:101] sc1
	s_waitcnt vmcnt(0)
	v_cmp_ne_u32_e32 vcc, 0, v1
	s_cbranch_vccz .Lq_fetch
	s_sleep 8
	s_add_i32 s25, s25, -1
	s_cmp_gt_i32 s25, 0
	s_cbranch_scc1 .Lq_spin2
.Lq_fetch:
	s_waitcnt vmcnt(6)
	s_lshl_b32 s25, s98, 4
	v_mov_b32_e32 v1, 1
	v_mov_b32_e32 v0, s25
	global_atomic_add v1, v0, v1, s[8:9] sc0
	s_waitcnt vmcnt(0)
	ds_write_b32 v131, v1 offset:43024
.Lq_sync:
	s_or_b64 exec, exec, s[0:1]
	s_waitcnt lgkmcnt(0)
	s_barrier
	s_waitcnt vmcnt(6)
	ds_read_b32 v0, v131 offset:43024
	s_movk_i32 s0, 0x80
	s_cmp_eq_u32 s98, 0
	s_cbranch_scc1 .Lq_lim
	s_movk_i32 s0, 0x700
.Lq_lim:
	s_waitcnt lgkmcnt(0)
	v_readfirstlane_b32 s25, v0
	s_nop 0
	s_cmp_lt_u32 s25, s0
	s_cbranch_scc1 .Lq_have
	s_cmp_eq_u32 s98, 0
	s_cbranch_scc0 .Lq_norel
	s_bitcmp1_b32 s99, 1
	s_cbranch_scc0 .Lq_norel
	s_andn2_b32 s99, s99, 2
	s_and_saveexec_b64 s[0:1], s[2:3]
	v_mov_b32_e32 v1, -1
	global_atomic_add v131, v1, s[100:101]
	s_or_b64 exec, exec, s[0:1]
.Lq_norel:
	s_bitcmp1_b32 s99, 0
	s_cbranch_scc1 .Lq_exit
	s_or_b32 s99, s99, 1
	s_xor_b32 s98, s98, 1
	s_branch .LBB0_102
.Lq_exit:
	v_readlane_b32 s2, v255, 31
	v_readlane_b32 s3, v255, 32
	s_mov_b64 s[0:1], -1
	s_branch .LBB0_101
.Lq_have:
	s_cmp_eq_u32 s98, 0
	s_cbranch_scc1 .Lq_go
	s_addk_i32 s25, 0x80
.Lq_go:
	v_readlane_b32 s2, v255, 31
	v_readlane_b32 s3, v255, 32
	s_mov_b64 s[0:1], -1
	s_cmpk_gt_i32 s25, 0x7f
	s_cbranch_scc0 .LBB0_139
	s_cmpk_gt_u32 s25, 0x47f
	s_cbranch_scc0 .LBB0_130
	s_cmpk_gt_u32 s25, 0x57f
	s_cbranch_scc0 .LBB0_125
	s_cmpk_gt_u32 s25, 0x5ff
	s_cbranch_scc0 .LBB0_120
	s_cmpk_gt_u32 s25, 0x6ff
	s_cbranch_scc0 .LBB0_115
	s_mov_b32 s26, 0
	s_add_i32 s27, s25, 0xfffff900
	s_branch .Lhy_common

.Lscan_w1:
	ds_write_b128 v26, v[146:149]
	ds_write_b128 v26, v[150:153] offset:256
	ds_write_b128 v26, v[154:157] offset:512
	ds_write_b128 v26, v[158:161] offset:768
	ds_write_b128 v26, v[162:165] offset:1024
	ds_write_b32 v27, v166
	s_add_i32 s0, s5, -1
	s_min_u32 s0, s0, 1
	s_mul_i32 s92, s0, s90
	v_add_u32_e32 v132, s92, v28
	v_add_u32_e32 v133, s92, v29
	v_add_u32_e32 v134, s92, v30
	v_add_u32_e32 v135, s92, v31
	v_add_u32_e32 v136, s92, v32
	v_add_u32_e32 v137, s92, v33
	s_waitcnt lgkmcnt(0)
	global_load_dwordx4 v[146:149], v132, s[96:97]
	global_load_dwordx4 v[150:153], v133, s[96:97]
	global_load_dwordx4 v[154:157], v134, s[96:97]
	global_load_dwordx4 v[158:161], v135, s[96:97]
	global_load_dwordx4 v[162:165], v136, s[96:97]
	global_load_dword v166, v137, s[96:97]
	s_mov_b32 s0, 2
	s_mul_i32 s92, s0, s90
	v_add_u32_e32 v132, s92, v28
	v_add_u32_e32 v133, s92, v29
	v_add_u32_e32 v134, s92, v30
	v_add_u32_e32 v135, s92, v31
	v_add_u32_e32 v136, s92, v32
	v_add_u32_e32 v137, s92, v33
	global_load_dwordx4 v[168:171], v132, s[96:97]
	global_load_dwordx4 v[172:175], v133, s[96:97]
	global_load_dwordx4 v[176:179], v134, s[96:97]
	global_load_dwordx4 v[180:183], v135, s[96:97]
	global_load_dwordx4 v[184:187], v136, s[96:97]
	global_load_dword v167, v137, s[96:97]
	s_barrier
	ds_read_b128 v[52:55], v139 offset:768
	ds_read_b32 v60, v140 offset:0
	ds_read_b128 v[44:47], v139 offset:256
	ds_read_b128 v[40:43], v139 offset:0
	ds_read_b128 v[48:51], v139 offset:512
	ds_read_b128 v[56:59], v139 offset:1024
	ds_read_b128 v[74:77], v139 offset:2112
	ds_read_b32 v82, v140 offset:1344
	ds_read_b128 v[66:69], v139 offset:1600
	ds_read_b128 v[62:65], v139 offset:1344
	ds_read_b128 v[70:73], v139 offset:1856
	ds_read_b128 v[78:81], v139 offset:2368
	s_waitcnt vmcnt(12)
	s_waitcnt lgkmcnt(6)
	v_mul_f32_e32 v8, v60, v52
	v_mul_f32_e32 v9, v60, v53
	v_mul_f32_e32 v10, v60, v54
	v_mul_f32_e32 v11, v60, v55

.Lscan_noy0:
	v_pk_mul_f32 v[16:17], v[0:1], v[66:67]
	v_pk_mul_f32 v[20:21], v[0:1], v[56:57]
	ds_read_b128 v[118:121], v139 offset:4800
	v_pk_fma_f32 v[16:17], v[2:3], v[68:69], v[16:17]
	v_pk_fma_f32 v[20:21], v[2:3], v[58:59], v[20:21]
	ds_read_b32 v126, v140 offset:4032
	v_add_f32_e32 v18, v16, v17
	v_add_f32_e32 v22, v20, v21
	v_pk_fma_f32 v[4:5], v[0:1], v[62:63], v[8:9]
	v_add_f32_dpp v18, v18, v18 quad_perm:[1,0,3,2] row_mask:0xf bank_mask:0xf bound_ctrl:1
	v_add_f32_dpp v22, v22, v22 quad_perm:[1,0,3,2] row_mask:0xf bank_mask:0xf bound_ctrl:1
	v_pk_fma_f32 v[6:7], v[2:3], v[64:65], v[10:11]
	v_add_f32_dpp v18, v18, v18 quad_perm:[2,3,0,1] row_mask:0xf bank_mask:0xf bound_ctrl:1
	v_add_f32_dpp v22, v22, v22 quad_perm:[2,3,0,1] row_mask:0xf bank_mask:0xf bound_ctrl:1
	ds_read_b128 v[110:113], v139 offset:4288
	v_add_f32_dpp v18, v18, v18 row_half_mirror row_mask:0xf bank_mask:0xf bound_ctrl:1
	v_add_f32_dpp v22, v22, v22 row_half_mirror row_mask:0xf bank_mask:0xf bound_ctrl:1
	ds_read_b128 v[106:109], v139 offset:4032
	v_add_f32_dpp v18, v18, v18 row_ror:8 row_mask:0xf bank_mask:0xf bound_ctrl:1
	v_add_f32_dpp v22, v22, v22 row_ror:8 row_mask:0xf bank_mask:0xf bound_ctrl:1
	ds_read_b128 v[114:117], v139 offset:4544
	v_pk_fma_f32 v[0:1], v[70:71], v[18:19], v[4:5] op_sel_hi:[1,0,1] neg_lo:[1,0,0] neg_hi:[1,0,0]
	v_pk_fma_f32 v[2:3], v[72:73], v[18:19], v[6:7] op_sel_hi:[1,0,1] neg_lo:[1,0,0] neg_hi:[1,0,0]
	v_cndmask_b32_e64 v23, v23, v22, s[36:37]
	ds_read_b128 v[122:125], v139 offset:5056
	s_waitcnt lgkmcnt(7)
	v_pk_mul_f32 v[8:9], v[96:97], v[104:105] op_sel_hi:[1,0]
	v_pk_mul_f32 v[10:11], v[98:99], v[104:105] op_sel_hi:[1,0]
	v_pk_mul_f32 v[16:17], v[0:1], v[88:89]
	v_pk_mul_f32 v[20:21], v[0:1], v[78:79]
	ds_read_b128 v[52:55], v139 offset:6144
	v_pk_fma_f32 v[16:17], v[2:3], v[90:91], v[16:17]
	v_pk_fma_f32 v[20:21], v[2:3], v[80:81], v[20:21]
	ds_read_b32 v60, v140 offset:5376
	v_add_f32_e32 v18, v16, v17
	v_add_f32_e32 v22, v20, v21
	v_pk_fma_f32 v[4:5], v[0:1], v[84:85], v[8:9]
	v_add_f32_dpp v18, v18, v18 quad_perm:[1,0,3,2] row_mask:0xf bank_mask:0xf bound_ctrl:1
	v_add_f32_dpp v22, v22, v22 quad_perm:[1,0,3,2] row_mask:0xf bank_mask:0xf bound_ctrl:1
	v_pk_fma_f32 v[6:7], v[2:3], v[86:87], v[10:11]
	v_add_f32_dpp v18, v18, v18 quad_perm:[2,3,0,1] row_mask:0xf bank_mask:0xf bound_ctrl:1
	v_add_f32_dpp v22, v22, v22 quad_perm:[2,3,0,1] row_mask:0xf bank_mask:0xf bound_ctrl:1
	ds_read_b128 v[44:47], v139 offset:5632
	v_add_f32_dpp v18, v18, v18 row_half_mirror row_mask:0xf bank_mask:0xf bound_ctrl:1
	v_add_f32_dpp v22, v22, v22 row_half_mirror row_mask:0xf bank_mask:0xf bound_ctrl:1
	ds_read_b128 v[40:43], v139 offset:5376
	v_add_f32_dpp v18, v18, v18 row_ror:8 row_mask:0xf bank_mask:0xf bound_ctrl:1
	v_add_f32_dpp v22, v22, v22 row_ror:8 row_mask:0xf bank_mask:0xf bound_ctrl:1
	ds_read_b128 v[48:51], v139 offset:5888
	v_pk_fma_f32 v[0:1], v[92:93], v[18:19], v[4:5] op_sel_hi:[1,0,1] neg_lo:[1,0,0] neg_hi:[1,0,0]
	v_pk_fma_f32 v[2:3], v[94:95], v[18:19], v[6:7] op_sel_hi:[1,0,1] neg_lo:[1,0,0] neg_hi:[1,0,0]
	v_cndmask_b32_e64 v23, v23, v22, s[38:39]
	ds_read_b128 v[56:59], v139 offset:6400
	s_waitcnt lgkmcnt(7)
	v_pk_mul_f32 v[8:9], v[118:119], v[126:127] op_sel_hi:[1,0]
	v_pk_mul_f32 v[10:11], v[120:121], v[126:127] op_sel_hi:[1,0]
	v_pk_mul_f32 v[16:17], v[0:1], v[110:111]
	v_pk_mul_f32 v[20:21], v[0:1], v[100:101]
	ds_read_b128 v[74:77], v139 offset:7488
	v_pk_fma_f32 v[16:17], v[2:3], v[112:113], v[16:17]
	v_pk_fma_f32 v[20:21], v[2:3], v[102:103], v[20:21]
	ds_read_b32 v82, v140 offset:6720
	v_add_f32_e32 v18, v16, v17
	v_add_f32_e32 v22, v20, v21
	v_pk_fma_f32 v[4:5], v[0:1], v[106:107], v[8:9]
	v_add_f32_dpp v18, v18, v18 quad_perm:[1,0,3,2] row_mask:0xf bank_mask:0xf bound_ctrl:1
	v_add_f32_dpp v22, v22, v22 quad_perm:[1,0,3,2] row_mask:0xf bank_mask:0xf bound_ctrl:1
	v_pk_fma_f32 v[6:7], v[2:3], v[108:109], v[10:11]
	v_add_f32_dpp v18, v18, v18 quad_perm:[2,3,0,1] row_mask:0xf bank_mask:0xf bound_ctrl:1
	v_add_f32_dpp v22, v22, v22 quad_perm:[2,3,0,1] row_mask:0xf bank_mask:0xf bound_ctrl:1
	ds_read_b128 v[66:69], v139 offset:6976
	v_add_f32_dpp v18, v18, v18 row_half_mirror row_mask:0xf bank_mask:0xf bound_ctrl:1
	v_add_f32_dpp v22, v22, v22 row_half_mirror row_mask:0xf bank_mask:0xf bound_ctrl:1
	ds_read_b128 v[62:65], v139 offset:6720
	v_add_f32_dpp v18, v18, v18 row_ror:8 row_mask:0xf bank_mask:0xf bound_ctrl:1
	v_add_f32_dpp v22, v22, v22 row_ror:8 row_mask:0xf bank_mask:0xf bound_ctrl:1
	ds_read_b128 v[70:73], v139 offset:7232
	v_pk_fma_f32 v[0:1], v[114:115], v[18:19], v[4:5] op_sel_hi:[1,0,1] neg_lo:[1,0,0] neg_hi:[1,0,0]
	v_pk_fma_f32 v[2:3], v[116:117], v[18:19], v[6:7] op_sel_hi:[1,0,1] neg_lo:[1,0,0] neg_hi:[1,0,0]
	v_cndmask_b32_e64 v23, v23, v22, s[40:41]
	ds_read_b128 v[78:81], v139 offset:7744
	s_waitcnt lgkmcnt(7)
	v_pk_mul_f32 v[8:9], v[52:53], v[60:61] op_sel_hi:[1,0]
	v_pk_mul_f32 v[10:11], v[54:55], v[60:61] op_sel_hi:[1,0]
	v_pk_mul_f32 v[16:17], v[0:1], v[44:45]
	v_pk_mul_f32 v[20:21], v[0:1], v[122:123]
	ds_read_b128 v[96:99], v139 offset:8832
	v_pk_fma_f32 v[16:17], v[2:3], v[46:47], v[16:17]
	v_pk_fma_f32 v[20:21], v[2:3], v[124:125], v[20:21]
	ds_read_b32 v104, v140 offset:8064
	v_add_f32_e32 v18, v16, v17
	v_add_f32_e32 v22, v20, v21
	v_pk_fma_f32 v[4:5], v[0:1], v[40:41], v[8:9]
	v_add_f32_dpp v18, v18, v18 quad_perm:[1,0,3,2] row_mask:0xf bank_mask:0xf bound_ctrl:1
	v_add_f32_dpp v22, v22, v22 quad_perm:[1,0,3,2] row_mask:0xf bank_mask:0xf bound_ctrl:1
	v_pk_fma_f32 v[6:7], v[2:3], v[42:43], v[10:11]
	v_add_f32_dpp v18, v18, v18 quad_perm:[2,3,0,1] row_mask:0xf bank_mask:0xf bound_ctrl:1
	v_add_f32_dpp v22, v22, v22 quad_perm:[2,3,0,1] row_mask:0xf bank_mask:0xf bound_ctrl:1
	ds_read_b128 v[88:91], v139 offset:8320
	v_add_f32_dpp v18, v18, v18 row_half_mirror row_mask:0xf bank_mask:0xf bound_ctrl:1
	v_add_f32_dpp v22, v22, v22 row_half_mirror row_mask:0xf bank_mask:0xf bound_ctrl:1
	ds_read_b128 v[84:87], v139 offset:8064
	v_add_f32_dpp v18, v18, v18 row_ror:8 row_mask:0xf bank_mask:0xf bound_ctrl:1
	v_add_f32_dpp v22, v22, v22 row_ror:8 row_mask:0xf bank_mask:0xf bound_ctrl:1
	ds_read_b128 v[92:95], v139 offset:8576
	v_pk_fma_f32 v[0:1], v[48:49], v[18:19], v[4:5] op_sel_hi:[1,0,1] neg_lo:[1,0,0] neg_hi:[1,0,0]
	v_pk_fma_f32 v[2:3], v[50:51], v[18:19], v[6:7] op_sel_hi:[1,0,1] neg_lo:[1,0,0] neg_hi:[1,0,0]
	v_cndmask_b32_e64 v23, v23, v22, s[42:43]
	ds_read_b128 v[100:103], v139 offset:9088
	s_waitcnt lgkmcnt(7)
	v_pk_mul_f32 v[8:9], v[74:75], v[82:83] op_sel_hi:[1,0]
	v_pk_mul_f32 v[10:11], v[76:77], v[82:83] op_sel_hi:[1,0]
	v_pk_mul_f32 v[16:17], v[0:1], v[66:67]
	v_pk_mul_f32 v[20:21], v[0:1], v[56:57]
	ds_read_b128 v[118:121], v139 offset:10176
	v_pk_fma_f32 v[16:17], v[2:3], v[68:69], v[16:17]
	v_pk_fma_f32 v[20:21], v[2:3], v[58:59], v[20:21]
	ds_read_b32 v126, v140 offset:9408
	v_add_f32_e32 v18, v16, v17
	v_add_f32_e32 v22, v20, v21
	v_pk_fma_f32 v[4:5], v[0:1], v[62:63], v[8:9]
	v_add_f32_dpp v18, v18, v18 quad_perm:[1,0,3,2] row_mask:0xf bank_mask:0xf bound_ctrl:1
	v_add_f32_dpp v22, v22, v22 quad_perm:[1,0,3,2] row_mask:0xf bank_mask:0xf bound_ctrl:1
	v_pk_fma_f32 v[6:7], v[2:3], v[64:65], v[10:11]
	v_add_f32_dpp v18, v18, v18 quad_perm:[2,3,0,1] row_mask:0xf bank_mask:0xf bound_ctrl:1
	v_add_f32_dpp v22, v22, v22 quad_perm:[2,3,0,1] row_mask:0xf bank_mask:0xf bound_ctrl:1
	ds_read_b128 v[110:113], v139 offset:9664
	v_add_f32_dpp v18, v18, v18 row_half_mirror row_mask:0xf bank_mask:0xf bound_ctrl:1
	v_add_f32_dpp v22, v22, v22 row_half_mirror row_mask:0xf bank_mask:0xf bound_ctrl:1
	ds_read_b128 v[106:109], v139 offset:9408
	v_add_f32_dpp v18, v18, v18 row_ror:8 row_mask:0xf bank_mask:0xf bound_ctrl:1
	v_add_f32_dpp v22, v22, v22 row_ror:8 row_mask:0xf bank_mask:0xf bound_ctrl:1
	ds_read_b128 v[114:117], v139 offset:9920
	v_pk_fma_f32 v[0:1], v[70:71], v[18:19], v[4:5] op_sel_hi:[1,0,1] neg_lo:[1,0,0] neg_hi:[1,0,0]
	v_pk_fma_f32 v[2:3], v[72:73], v[18:19], v[6:7] op_sel_hi:[1,0,1] neg_lo:[1,0,0] neg_hi:[1,0,0]
	v_cndmask_b32_e64 v23, v23, v22, s[44:45]
	ds_read_b128 v[122:125], v139 offset:10432
	s_waitcnt lgkmcnt(7)
	v_pk_mul_f32 v[8:9], v[96:97], v[104:105] op_sel_hi:[1,0]
	v_pk_mul_f32 v[10:11], v[98:99], v[104:105] op_sel_hi:[1,0]
	v_pk_mul_f32 v[16:17], v[0:1], v[88:89]
	v_pk_mul_f32 v[20:21], v[0:1], v[78:79]
	ds_read_b128 v[52:55], v139 offset:11520
	v_pk_fma_f32 v[16:17], v[2:3], v[90:91], v[16:17]
	v_pk_fma_f32 v[20:21], v[2:3], v[80:81], v[20:21]
	ds_read_b32 v60, v140 offset:10752
	v_add_f32_e32 v18, v16, v17
	v_add_f32_e32 v22, v20, v21
	v_pk_fma_f32 v[4:5], v[0:1], v[84:85], v[8:9]
	v_add_f32_dpp v18, v18, v18 quad_perm:[1,0,3,2] row_mask:0xf bank_mask:0xf bound_ctrl:1
	v_add_f32_dpp v22, v22, v22 quad_perm:[1,0,3,2] row_mask:0xf bank_mask:0xf bound_ctrl:1
	v_pk_fma_f32 v[6:7], v[2:3], v[86:87], v[10:11]
	v_add_f32_dpp v18, v18, v18 quad_perm:[2,3,0,1] row_mask:0xf bank_mask:0xf bound_ctrl:1
	v_add_f32_dpp v22, v22, v22 quad_perm:[2,3,0,1] row_mask:0xf bank_mask:0xf bound_ctrl:1
	ds_read_b128 v[44:47], v139 offset:11008
	v_add_f32_dpp v18, v18, v18 row_half_mirror row_mask:0xf bank_mask:0xf bound_ctrl:1
	v_add_f32_dpp v22, v22, v22 row_half_mirror row_mask:0xf bank_mask:0xf bound_ctrl:1
	ds_read_b128 v[40:43], v139 offset:10752
	v_add_f32_dpp v18, v18, v18 row_ror:8 row_mask:0xf bank_mask:0xf bound_ctrl:1
	v_add_f32_dpp v22, v22, v22 row_ror:8 row_mask:0xf bank_mask:0xf bound_ctrl:1
	ds_read_b128 v[48:51], v139 offset:11264
	v_pk_fma_f32 v[0:1], v[92:93], v[18:19], v[4:5] op_sel_hi:[1,0,1] neg_lo:[1,0,0] neg_hi:[1,0,0]
	v_pk_fma_f32 v[2:3], v[94:95], v[18:19], v[6:7] op_sel_hi:[1,0,1] neg_lo:[1,0,0] neg_hi:[1,0,0]
	v_cndmask_b32_e64 v23, v23, v22, s[46:47]
	ds_read_b128 v[56:59], v139 offset:11776
	s_waitcnt lgkmcnt(7)
	v_pk_mul_f32 v[8:9], v[118:119], v[126:127] op_sel_hi:[1,0]
	v_pk_mul_f32 v[10:11], v[120:121], v[126:127] op_sel_hi:[1,0]
	v_pk_mul_f32 v[16:17], v[0:1], v[110:111]
	v_pk_mul_f32 v[20:21], v[0:1], v[100:101]
	ds_read_b128 v[74:77], v139 offset:12864
	v_pk_fma_f32 v[16:17], v[2:3], v[112:113], v[16:17]
	v_pk_fma_f32 v[20:21], v[2:3], v[102:103], v[20:21]
	ds_read_b32 v82, v140 offset:12096
	v_add_f32_e32 v18, v16, v17
	v_add_f32_e32 v22, v20, v21
	v_pk_fma_f32 v[4:5], v[0:1], v[106:107], v[8:9]
	v_add_f32_dpp v18, v18, v18 quad_perm:[1,0,3,2] row_mask:0xf bank_mask:0xf bound_ctrl:1
	v_add_f32_dpp v22, v22, v22 quad_perm:[1,0,3,2] row_mask:0xf bank_mask:0xf bound_ctrl:1
	v_pk_fma_f32 v[6:7], v[2:3], v[108:109], v[10:11]
	v_add_f32_dpp v18, v18, v18 quad_perm:[2,3,0,1] row_mask:0xf bank_mask:0xf bound_ctrl:1
	v_add_f32_dpp v22, v22, v22 quad_perm:[2,3,0,1] row_mask:0xf bank_mask:0xf bound_ctrl:1
	ds_read_b128 v[66:69], v139 offset:12352
	v_add_f32_dpp v18, v18, v18 row_half_mirror row_mask:0xf bank_mask:0xf bound_ctrl:1
	v_add_f32_dpp v22, v22, v22 row_half_mirror row_mask:0xf bank_mask:0xf bound_ctrl:1
	ds_read_b128 v[62:65], v139 offset:12096
	v_add_f32_dpp v18, v18, v18 row_ror:8 row_mask:0xf bank_mask:0xf bound_ctrl:1
	v_add_f32_dpp v22, v22, v22 row_ror:8 row_mask:0xf bank_mask:0xf bound_ctrl:1
	ds_read_b128 v[70:73], v139 offset:12608
	v_pk_fma_f32 v[0:1], v[114:115], v[18:19], v[4:5] op_sel_hi:[1,0,1] neg_lo:[1,0,0] neg_hi:[1,0,0]
	v_pk_fma_f32 v[2:3], v[116:117], v[18:19], v[6:7] op_sel_hi:[1,0,1] neg_lo:[1,0,0] neg_hi:[1,0,0]
	v_cndmask_b32_e64 v23, v23, v22, s[48:49]
	ds_read_b128 v[78:81], v139 offset:13120
	s_waitcnt lgkmcnt(7)
	v_pk_mul_f32 v[8:9], v[52:53], v[60:61] op_sel_hi:[1,0]
	v_pk_mul_f32 v[10:11], v[54:55], v[60:61] op_sel_hi:[1,0]
	v_pk_mul_f32 v[16:17], v[0:1], v[44:45]
	v_pk_mul_f32 v[20:21], v[0:1], v[122:123]
	ds_read_b128 v[96:99], v139 offset:14208
	v_pk_fma_f32 v[16:17], v[2:3], v[46:47], v[16:17]
	v_pk_fma_f32 v[20:21], v[2:3], v[124:125], v[20:21]
	ds_read_b32 v104, v140 offset:13440
	v_add_f32_e32 v18, v16, v17
	v_add_f32_e32 v22, v20, v21
	v_pk_fma_f32 v[4:5], v[0:1], v[40:41], v[8:9]
	v_add_f32_dpp v18, v18, v18 quad_perm:[1,0,3,2] row_mask:0xf bank_mask:0xf bound_ctrl:1
	v_add_f32_dpp v22, v22, v22 quad_perm:[1,0,3,2] row_mask:0xf bank_mask:0xf bound_ctrl:1
	v_pk_fma_f32 v[6:7], v[2:3], v[42:43], v[10:11]
	v_add_f32_dpp v18, v18, v18 quad_perm:[2,3,0,1] row_mask:0xf bank_mask:0xf bound_ctrl:1
	v_add_f32_dpp v22, v22, v22 quad_perm:[2,3,0,1] row_mask:0xf bank_mask:0xf bound_ctrl:1
	ds_read_b128 v[88:91], v139 offset:13696
	v_add_f32_dpp v18, v18, v18 row_half_mirror row_mask:0xf bank_mask:0xf bound_ctrl:1
	v_add_f32_dpp v22, v22, v22 row_half_mirror row_mask:0xf bank_mask:0xf bound_ctrl:1
	ds_read_b128 v[84:87], v139 offset:13440
	v_add_f32_dpp v18, v18, v18 row_ror:8 row_mask:0xf bank_mask:0xf bound_ctrl:1
	v_add_f32_dpp v22, v22, v22 row_ror:8 row_mask:0xf bank_mask:0xf bound_ctrl:1
	ds_read_b128 v[92:95], v139 offset:13952
	v_pk_fma_f32 v[0:1], v[48:49], v[18:19], v[4:5] op_sel_hi:[1,0,1] neg_lo:[1,0,0] neg_hi:[1,0,0]
	v_pk_fma_f32 v[2:3], v[50:51], v[18:19], v[6:7] op_sel_hi:[1,0,1] neg_lo:[1,0,0] neg_hi:[1,0,0]
	v_cndmask_b32_e64 v23, v23, v22, s[50:51]
	ds_read_b128 v[100:103], v139 offset:14464
	s_waitcnt lgkmcnt(7)
	v_pk_mul_f32 v[8:9], v[74:75], v[82:83] op_sel_hi:[1,0]
	v_pk_mul_f32 v[10:11], v[76:77], v[82:83] op_sel_hi:[1,0]
	v_pk_mul_f32 v[16:17], v[0:1], v[66:67]
	v_pk_mul_f32 v[20:21], v[0:1], v[56:57]
	ds_read_b128 v[118:121], v139 offset:15552
	v_pk_fma_f32 v[16:17], v[2:3], v[68:69], v[16:17]
	v_pk_fma_f32 v[20:21], v[2:3], v[58:59], v[20:21]
	ds_read_b32 v126, v140 offset:14784
	v_add_f32_e32 v18, v16, v17
	v_add_f32_e32 v22, v20, v21
	v_pk_fma_f32 v[4:5], v[0:1], v[62:63], v[8:9]
	v_add_f32_dpp v18, v18, v18 quad_perm:[1,0,3,2] row_mask:0xf bank_mask:0xf bound_ctrl:1
	v_add_f32_dpp v22, v22, v22 quad_perm:[1,0,3,2] row_mask:0xf bank_mask:0xf bound_ctrl:1
	v_pk_fma_f32 v[6:7], v[2:3], v[64:65], v[10:11]
	v_add_f32_dpp v18, v18, v18 quad_perm:[2,3,0,1] row_mask:0xf bank_mask:0xf bound_ctrl:1
	v_add_f32_dpp v22, v22, v22 quad_perm:[2,3,0,1] row_mask:0xf bank_mask:0xf bound_ctrl:1
	ds_read_b128 v[110:113], v139 offset:15040
	v_add_f32_dpp v18, v18, v18 row_half_mirror row_mask:0xf bank_mask:0xf bound_ctrl:1
	v_add_f32_dpp v22, v22, v22 row_half_mirror row_mask:0xf bank_mask:0xf bound_ctrl:1
	ds_read_b128 v[106:109], v139 offset:14784
	v_add_f32_dpp v18, v18, v18 row_ror:8 row_mask:0xf bank_mask:0xf bound_ctrl:1
	v_add_f32_dpp v22, v22, v22 row_ror:8 row_mask:0xf bank_mask:0xf bound_ctrl:1
	ds_read_b128 v[114:117], v139 offset:15296
	v_pk_fma_f32 v[0:1], v[70:71], v[18:19], v[4:5] op_sel_hi:[1,0,1] neg_lo:[1,0,0] neg_hi:[1,0,0]
	v_pk_fma_f32 v[2:3], v[72:73], v[18:19], v[6:7] op_sel_hi:[1,0,1] neg_lo:[1,0,0] neg_hi:[1,0,0]
	v_cndmask_b32_e64 v23, v23, v22, s[52:53]
	ds_read_b128 v[122:125], v139 offset:15808
	s_waitcnt lgkmcnt(7)
	v_pk_mul_f32 v[8:9], v[96:97], v[104:105] op_sel_hi:[1,0]
	v_pk_mul_f32 v[10:11], v[98:99], v[104:105] op_sel_hi:[1,0]
	v_pk_mul_f32 v[16:17], v[0:1], v[88:89]
	v_pk_mul_f32 v[20:21], v[0:1], v[78:79]
	ds_read_b128 v[52:55], v139 offset:16896
	v_pk_fma_f32 v[16:17], v[2:3], v[90:91], v[16:17]
	v_pk_fma_f32 v[20:21], v[2:3], v[80:81], v[20:21]
	ds_read_b32 v60, v140 offset:16128
	v_add_f32_e32 v18, v16, v17
	v_add_f32_e32 v22, v20, v21
	v_pk_fma_f32 v[4:5], v[0:1], v[84:85], v[8:9]
	v_add_f32_dpp v18, v18, v18 quad_perm:[1,0,3,2] row_mask:0xf bank_mask:0xf bound_ctrl:1
	v_add_f32_dpp v22, v22, v22 quad_perm:[1,0,3,2] row_mask:0xf bank_mask:0xf bound_ctrl:1
	v_pk_fma_f32 v[6:7], v[2:3], v[86:87], v[10:11]
	v_add_f32_dpp v18, v18, v18 quad_perm:[2,3,0,1] row_mask:0xf bank_mask:0xf bound_ctrl:1
	v_add_f32_dpp v22, v22, v22 quad_perm:[2,3,0,1] row_mask:0xf bank_mask:0xf bound_ctrl:1
	ds_read_b128 v[44:47], v139 offset:16384
	v_add_f32_dpp v18, v18, v18 row_half_mirror row_mask:0xf bank_mask:0xf bound_ctrl:1
	v_add_f32_dpp v22, v22, v22 row_half_mirror row_mask:0xf bank_mask:0xf bound_ctrl:1
	ds_read_b128 v[40:43], v139 offset:16128
	v_add_f32_dpp v18, v18, v18 row_ror:8 row_mask:0xf bank_mask:0xf bound_ctrl:1
	v_add_f32_dpp v22, v22, v22 row_ror:8 row_mask:0xf bank_mask:0xf bound_ctrl:1
	ds_read_b128 v[48:51], v139 offset:16640
	v_pk_fma_f32 v[0:1], v[92:93], v[18:19], v[4:5] op_sel_hi:[1,0,1] neg_lo:[1,0,0] neg_hi:[1,0,0]
	v_pk_fma_f32 v[2:3], v[94:95], v[18:19], v[6:7] op_sel_hi:[1,0,1] neg_lo:[1,0,0] neg_hi:[1,0,0]
	v_cndmask_b32_e64 v23, v23, v22, s[54:55]
	ds_read_b128 v[56:59], v139 offset:17152
	s_waitcnt lgkmcnt(7)
	v_pk_mul_f32 v[8:9], v[118:119], v[126:127] op_sel_hi:[1,0]
	v_pk_mul_f32 v[10:11], v[120:121], v[126:127] op_sel_hi:[1,0]
	s_add_i32 s0, s4, 2
	s_cmp_lt_u32 s0, s5
	s_cbranch_scc1 .Lscan_w6_0
	s_waitcnt vmcnt(0)
	s_branch .Lscan_wd_0

.Lscan_wd_0:
	ds_write_b128 v143, v[146:149]
	ds_write_b128 v143, v[150:153] offset:256
	ds_write_b128 v143, v[154:157] offset:512
	ds_write_b128 v143, v[158:161] offset:768
	ds_write_b128 v143, v[162:165] offset:1024
	ds_write_b32 v35, v166
	v_pk_mul_f32 v[16:17], v[0:1], v[110:111]
	v_pk_mul_f32 v[20:21], v[0:1], v[100:101]
	ds_read_b128 v[74:77], v139 offset:18240
	v_pk_fma_f32 v[16:17], v[2:3], v[112:113], v[16:17]
	v_pk_fma_f32 v[20:21], v[2:3], v[102:103], v[20:21]
	ds_read_b32 v82, v140 offset:17472
	v_add_f32_e32 v18, v16, v17
	v_add_f32_e32 v22, v20, v21
	v_pk_fma_f32 v[4:5], v[0:1], v[106:107], v[8:9]
	v_add_f32_dpp v18, v18, v18 quad_perm:[1,0,3,2] row_mask:0xf bank_mask:0xf bound_ctrl:1
	v_add_f32_dpp v22, v22, v22 quad_perm:[1,0,3,2] row_mask:0xf bank_mask:0xf bound_ctrl:1
	v_pk_fma_f32 v[6:7], v[2:3], v[108:109], v[10:11]
	v_add_f32_dpp v18, v18, v18 quad_perm:[2,3,0,1] row_mask:0xf bank_mask:0xf bound_ctrl:1
	v_add_f32_dpp v22, v22, v22 quad_perm:[2,3,0,1] row_mask:0xf bank_mask:0xf bound_ctrl:1
	ds_read_b128 v[66:69], v139 offset:17728
	v_add_f32_dpp v18, v18, v18 row_half_mirror row_mask:0xf bank_mask:0xf bound_ctrl:1
	v_add_f32_dpp v22, v22, v22 row_half_mirror row_mask:0xf bank_mask:0xf bound_ctrl:1
	ds_read_b128 v[62:65], v139 offset:17472
	v_add_f32_dpp v18, v18, v18 row_ror:8 row_mask:0xf bank_mask:0xf bound_ctrl:1
	v_add_f32_dpp v22, v22, v22 row_ror:8 row_mask:0xf bank_mask:0xf bound_ctrl:1
	ds_read_b128 v[70:73], v139 offset:17984
	v_pk_fma_f32 v[0:1], v[114:115], v[18:19], v[4:5] op_sel_hi:[1,0,1] neg_lo:[1,0,0] neg_hi:[1,0,0]
	v_pk_fma_f32 v[2:3], v[116:117], v[18:19], v[6:7] op_sel_hi:[1,0,1] neg_lo:[1,0,0] neg_hi:[1,0,0]
	v_cndmask_b32_e64 v23, v23, v22, s[56:57]
	ds_read_b128 v[78:81], v139 offset:18496
	s_waitcnt lgkmcnt(7)
	v_pk_mul_f32 v[8:9], v[52:53], v[60:61] op_sel_hi:[1,0]
	v_pk_mul_f32 v[10:11], v[54:55], v[60:61] op_sel_hi:[1,0]
	v_pk_mul_f32 v[16:17], v[0:1], v[44:45]
	v_pk_mul_f32 v[20:21], v[0:1], v[122:123]
	ds_read_b128 v[96:99], v139 offset:19584
	v_pk_fma_f32 v[16:17], v[2:3], v[46:47], v[16:17]
	v_pk_fma_f32 v[20:21], v[2:3], v[124:125], v[20:21]
	ds_read_b32 v104, v140 offset:18816
	v_add_f32_e32 v18, v16, v17
	v_add_f32_e32 v22, v20, v21
	v_pk_fma_f32 v[4:5], v[0:1], v[40:41], v[8:9]
	v_add_f32_dpp v18, v18, v18 quad_perm:[1,0,3,2] row_mask:0xf bank_mask:0xf bound_ctrl:1
	v_add_f32_dpp v22, v22, v22 quad_perm:[1,0,3,2] row_mask:0xf bank_mask:0xf bound_ctrl:1
	v_pk_fma_f32 v[6:7], v[2:3], v[42:43], v[10:11]
	v_add_f32_dpp v18, v18, v18 quad_perm:[2,3,0,1] row_mask:0xf bank_mask:0xf bound_ctrl:1
	v_add_f32_dpp v22, v22, v22 quad_perm:[2,3,0,1] row_mask:0xf bank_mask:0xf bound_ctrl:1
	ds_read_b128 v[88:91], v139 offset:19072
	v_add_f32_dpp v18, v18, v18 row_half_mirror row_mask:0xf bank_mask:0xf bound_ctrl:1
	v_add_f32_dpp v22, v22, v22 row_half_mirror row_mask:0xf bank_mask:0xf bound_ctrl:1
	ds_read_b128 v[84:87], v139 offset:18816
	v_add_f32_dpp v18, v18, v18 row_ror:8 row_mask:0xf bank_mask:0xf bound_ctrl:1
	v_add_f32_dpp v22, v22, v22 row_ror:8 row_mask:0xf bank_mask:0xf bound_ctrl:1
	ds_read_b128 v[92:95], v139 offset:19328
	v_pk_fma_f32 v[0:1], v[48:49], v[18:19], v[4:5] op_sel_hi:[1,0,1] neg_lo:[1,0,0] neg_hi:[1,0,0]
	v_pk_fma_f32 v[2:3], v[50:51], v[18:19], v[6:7] op_sel_hi:[1,0,1] neg_lo:[1,0,0] neg_hi:[1,0,0]
	v_cndmask_b32_e64 v23, v23, v22, s[58:59]
	ds_read_b128 v[100:103], v139 offset:19840
	s_waitcnt lgkmcnt(7)
	s_barrier
	s_add_i32 s0, s4, 3
	s_cmp_lt_u32 s0, s5
	s_cbranch_scc0 .Lscan_nold0
	s_mul_i32 s92, s0, s90
	v_add_u32_e32 v132, s92, v28
	v_add_u32_e32 v133, s92, v29
	v_add_u32_e32 v134, s92, v30
	v_add_u32_e32 v135, s92, v31
	v_add_u32_e32 v136, s92, v32
	v_add_u32_e32 v137, s92, v33
	global_load_dwordx4 v[146:149], v132, s[96:97]
	global_load_dwordx4 v[150:153], v133, s[96:97]
	global_load_dwordx4 v[154:157], v134, s[96:97]
	global_load_dwordx4 v[158:161], v135, s[96:97]
	global_load_dwordx4 v[162:165], v136, s[96:97]
	global_load_dword v166, v137, s[96:97]
.Lscan_nold0:
	v_pk_mul_f32 v[8:9], v[74:75], v[82:83] op_sel_hi:[1,0]
	v_pk_mul_f32 v[10:11], v[76:77], v[82:83] op_sel_hi:[1,0]
	v_pk_mul_f32 v[16:17], v[0:1], v[66:67]
	v_pk_mul_f32 v[20:21], v[0:1], v[56:57]
	ds_read_b128 v[118:121], v139 offset:20928
	v_pk_fma_f32 v[16:17], v[2:3], v[68:69], v[16:17]
	v_pk_fma_f32 v[20:21], v[2:3], v[58:59], v[20:21]
	ds_read_b32 v126, v140 offset:20160
	v_add_f32_e32 v18, v16, v17
	v_add_f32_e32 v22, v20, v21
	v_pk_fma_f32 v[4:5], v[0:1], v[62:63], v[8:9]
	v_add_f32_dpp v18, v18, v18 quad_perm:[1,0,3,2] row_mask:0xf bank_mask:0xf bound_ctrl:1
	v_add_f32_dpp v22, v22, v22 quad_perm:[1,0,3,2] row_mask:0xf bank_mask:0xf bound_ctrl:1
	v_pk_fma_f32 v[6:7], v[2:3], v[64:65], v[10:11]
	v_add_f32_dpp v18, v18, v18 quad_perm:[2,3,0,1] row_mask:0xf bank_mask:0xf bound_ctrl:1
	v_add_f32_dpp v22, v22, v22 quad_perm:[2,3,0,1] row_mask:0xf bank_mask:0xf bound_ctrl:1
	ds_read_b128 v[110:113], v139 offset:20416
	v_add_f32_dpp v18, v18, v18 row_half_mirror row_mask:0xf bank_mask:0xf bound_ctrl:1
	v_add_f32_dpp v22, v22, v22 row_half_mirror row_mask:0xf bank_mask:0xf bound_ctrl:1
	ds_read_b128 v[106:109], v139 offset:20160
	v_add_f32_dpp v18, v18, v18 row_ror:8 row_mask:0xf bank_mask:0xf bound_ctrl:1
	v_add_f32_dpp v22, v22, v22 row_ror:8 row_mask:0xf bank_mask:0xf bound_ctrl:1
	ds_read_b128 v[114:117], v139 offset:20672
	v_pk_fma_f32 v[0:1], v[70:71], v[18:19], v[4:5] op_sel_hi:[1,0,1] neg_lo:[1,0,0] neg_hi:[1,0,0]
	v_pk_fma_f32 v[2:3], v[72:73], v[18:19], v[6:7] op_sel_hi:[1,0,1] neg_lo:[1,0,0] neg_hi:[1,0,0]
	v_cndmask_b32_e64 v23, v23, v22, s[60:61]
	ds_read_b128 v[122:125], v139 offset:21184
	s_waitcnt lgkmcnt(7)
	v_pk_mul_f32 v[8:9], v[96:97], v[104:105] op_sel_hi:[1,0]
	v_pk_mul_f32 v[10:11], v[98:99], v[104:105] op_sel_hi:[1,0]
	v_pk_mul_f32 v[16:17], v[0:1], v[88:89]
	v_pk_mul_f32 v[20:21], v[0:1], v[78:79]
	ds_read_b128 v[52:55], v141 offset:768
	v_pk_fma_f32 v[16:17], v[2:3], v[90:91], v[16:17]
	v_pk_fma_f32 v[20:21], v[2:3], v[80:81], v[20:21]
	ds_read_b32 v60, v142 offset:0
	v_add_f32_e32 v18, v16, v17
	v_add_f32_e32 v22, v20, v21
	v_pk_fma_f32 v[4:5], v[0:1], v[84:85], v[8:9]
	v_add_f32_dpp v18, v18, v18 quad_perm:[1,0,3,2] row_mask:0xf bank_mask:0xf bound_ctrl:1
	v_add_f32_dpp v22, v22, v22 quad_perm:[1,0,3,2] row_mask:0xf bank_mask:0xf bound_ctrl:1
	v_pk_fma_f32 v[6:7], v[2:3], v[86:87], v[10:11]
	v_add_f32_dpp v18, v18, v18 quad_perm:[2,3,0,1] row_mask:0xf bank_mask:0xf bound_ctrl:1
	v_add_f32_dpp v22, v22, v22 quad_perm:[2,3,0,1] row_mask:0xf bank_mask:0xf bound_ctrl:1
	ds_read_b128 v[44:47], v141 offset:256
	v_add_f32_dpp v18, v18, v18 row_half_mirror row_mask:0xf bank_mask:0xf bound_ctrl:1
	v_add_f32_dpp v22, v22, v22 row_half_mirror row_mask:0xf bank_mask:0xf bound_ctrl:1
	ds_read_b128 v[40:43], v141 offset:0
	v_add_f32_dpp v18, v18, v18 row_ror:8 row_mask:0xf bank_mask:0xf bound_ctrl:1
	v_add_f32_dpp v22, v22, v22 row_ror:8 row_mask:0xf bank_mask:0xf bound_ctrl:1
	ds_read_b128 v[48:51], v141 offset:512
	v_pk_fma_f32 v[0:1], v[92:93], v[18:19], v[4:5] op_sel_hi:[1,0,1] neg_lo:[1,0,0] neg_hi:[1,0,0]
	v_pk_fma_f32 v[2:3], v[94:95], v[18:19], v[6:7] op_sel_hi:[1,0,1] neg_lo:[1,0,0] neg_hi:[1,0,0]
	v_cndmask_b32_e64 v23, v23, v22, s[62:63]
	ds_read_b128 v[56:59], v141 offset:1024
	s_waitcnt lgkmcnt(7)
	v_pk_mul_f32 v[8:9], v[118:119], v[126:127] op_sel_hi:[1,0]
	v_pk_mul_f32 v[10:11], v[120:121], v[126:127] op_sel_hi:[1,0]
	v_pk_mul_f32 v[16:17], v[0:1], v[110:111]
	v_pk_mul_f32 v[20:21], v[0:1], v[100:101]
	ds_read_b128 v[74:77], v141 offset:2112
	v_pk_fma_f32 v[16:17], v[2:3], v[112:113], v[16:17]
	v_pk_fma_f32 v[20:21], v[2:3], v[102:103], v[20:21]
	ds_read_b32 v82, v142 offset:1344
	v_add_f32_e32 v18, v16, v17
	v_add_f32_e32 v22, v20, v21
	v_pk_fma_f32 v[4:5], v[0:1], v[106:107], v[8:9]
	v_add_f32_dpp v18, v18, v18 quad_perm:[1,0,3,2] row_mask:0xf bank_mask:0xf bound_ctrl:1
	v_add_f32_dpp v22, v22, v22 quad_perm:[1,0,3,2] row_mask:0xf bank_mask:0xf bound_ctrl:1
	v_pk_fma_f32 v[6:7], v[2:3], v[108:109], v[10:11]
	v_add_f32_dpp v18, v18, v18 quad_perm:[2,3,0,1] row_mask:0xf bank_mask:0xf bound_ctrl:1
	v_add_f32_dpp v22, v22, v22 quad_perm:[2,3,0,1] row_mask:0xf bank_mask:0xf bound_ctrl:1
	ds_read_b128 v[66:69], v141 offset:1600
	v_add_f32_dpp v18, v18, v18 row_half_mirror row_mask:0xf bank_mask:0xf bound_ctrl:1
	v_add_f32_dpp v22, v22, v22 row_half_mirror row_mask:0xf bank_mask:0xf bound_ctrl:1
	ds_read_b128 v[62:65], v141 offset:1344
	v_add_f32_dpp v18, v18, v18 row_ror:8 row_mask:0xf bank_mask:0xf bound_ctrl:1
	v_add_f32_dpp v22, v22, v22 row_ror:8 row_mask:0xf bank_mask:0xf bound_ctrl:1
	ds_read_b128 v[70:73], v141 offset:1856
	v_pk_fma_f32 v[0:1], v[114:115], v[18:19], v[4:5] op_sel_hi:[1,0,1] neg_lo:[1,0,0] neg_hi:[1,0,0]
	v_pk_fma_f32 v[2:3], v[116:117], v[18:19], v[6:7] op_sel_hi:[1,0,1] neg_lo:[1,0,0] neg_hi:[1,0,0]
	v_cndmask_b32_e64 v23, v23, v22, s[64:65]
	ds_read_b128 v[78:81], v141 offset:2368
	s_waitcnt lgkmcnt(7)
	v_pk_mul_f32 v[8:9], v[52:53], v[60:61] op_sel_hi:[1,0]
	v_pk_mul_f32 v[10:11], v[54:55], v[60:61] op_sel_hi:[1,0]
	s_add_i32 s4, s4, 1
	s_mov_b32 s0, s6
	s_mov_b32 s6, s7
	s_mov_b32 s7, s25
	s_mov_b32 s25, s0
	v_mov_b32_e32 v139, v141
	v_mov_b32_e32 v140, v142
	v_add_u32_e32 v141, s7, v24
	v_add_u32_e32 v142, s7, v25
	v_add_u32_e32 v143, s7, v26
	v_add_u32_e32 v35, s7, v27
	v_pk_mul_f32 v[16:17], v[0:1], v[44:45]
	v_pk_mul_f32 v[20:21], v[0:1], v[122:123]
	ds_read_b128 v[96:99], v139 offset:3456
	v_pk_fma_f32 v[16:17], v[2:3], v[46:47], v[16:17]
	v_pk_fma_f32 v[20:21], v[2:3], v[124:125], v[20:21]
	ds_read_b32 v104, v140 offset:2688
	v_add_f32_e32 v18, v16, v17
	v_add_f32_e32 v22, v20, v21
	v_pk_fma_f32 v[4:5], v[0:1], v[40:41], v[8:9]
	v_add_f32_dpp v18, v18, v18 quad_perm:[1,0,3,2] row_mask:0xf bank_mask:0xf bound_ctrl:1
	v_add_f32_dpp v22, v22, v22 quad_perm:[1,0,3,2] row_mask:0xf bank_mask:0xf bound_ctrl:1
	v_pk_fma_f32 v[6:7], v[2:3], v[42:43], v[10:11]
	v_add_f32_dpp v18, v18, v18 quad_perm:[2,3,0,1] row_mask:0xf bank_mask:0xf bound_ctrl:1
	v_add_f32_dpp v22, v22, v22 quad_perm:[2,3,0,1] row_mask:0xf bank_mask:0xf bound_ctrl:1
	ds_read_b128 v[88:91], v139 offset:2944
	v_add_f32_dpp v18, v18, v18 row_half_mirror row_mask:0xf bank_mask:0xf bound_ctrl:1
	v_add_f32_dpp v22, v22, v22 row_half_mirror row_mask:0xf bank_mask:0xf bound_ctrl:1
	ds_read_b128 v[84:87], v139 offset:2688
	v_add_f32_dpp v18, v18, v18 row_ror:8 row_mask:0xf bank_mask:0xf bound_ctrl:1
	v_add_f32_dpp v22, v22, v22 row_ror:8 row_mask:0xf bank_mask:0xf bound_ctrl:1
	ds_read_b128 v[92:95], v139 offset:3200
	v_pk_fma_f32 v[0:1], v[48:49], v[18:19], v[4:5] op_sel_hi:[1,0,1] neg_lo:[1,0,0] neg_hi:[1,0,0]
	v_pk_fma_f32 v[2:3], v[50:51], v[18:19], v[6:7] op_sel_hi:[1,0,1] neg_lo:[1,0,0] neg_hi:[1,0,0]
	v_cndmask_b32_e64 v23, v23, v22, s[66:67]
	ds_read_b128 v[100:103], v139 offset:3712
	s_waitcnt lgkmcnt(7)
	v_pk_mul_f32 v[8:9], v[74:75], v[82:83] op_sel_hi:[1,0]
	v_pk_mul_f32 v[10:11], v[76:77], v[82:83] op_sel_hi:[1,0]
	s_cmp_eq_u32 s4, 0
	s_cbranch_scc1 .Lscan_noy1
	global_store_dword v138, v23, s[96:97]
	v_add_u32_e32 v138, s90, v138

.Lscan_wd_1:
	ds_write_b128 v143, v[168:171]
	ds_write_b128 v143, v[172:175] offset:256
	ds_write_b128 v143, v[176:179] offset:512
	ds_write_b128 v143, v[180:183] offset:768
	ds_write_b128 v143, v[184:187] offset:1024
	ds_write_b32 v35, v167
	v_pk_mul_f32 v[16:17], v[0:1], v[110:111]
	v_pk_mul_f32 v[20:21], v[0:1], v[100:101]
	ds_read_b128 v[74:77], v139 offset:18240
	v_pk_fma_f32 v[16:17], v[2:3], v[112:113], v[16:17]
	v_pk_fma_f32 v[20:21], v[2:3], v[102:103], v[20:21]
	ds_read_b32 v82, v140 offset:17472
	v_add_f32_e32 v18, v16, v17
	v_add_f32_e32 v22, v20, v21
	v_pk_fma_f32 v[4:5], v[0:1], v[106:107], v[8:9]
	v_add_f32_dpp v18, v18, v18 quad_perm:[1,0,3,2] row_mask:0xf bank_mask:0xf bound_ctrl:1
	v_add_f32_dpp v22, v22, v22 quad_perm:[1,0,3,2] row_mask:0xf bank_mask:0xf bound_ctrl:1
	v_pk_fma_f32 v[6:7], v[2:3], v[108:109], v[10:11]
	v_add_f32_dpp v18, v18, v18 quad_perm:[2,3,0,1] row_mask:0xf bank_mask:0xf bound_ctrl:1
	v_add_f32_dpp v22, v22, v22 quad_perm:[2,3,0,1] row_mask:0xf bank_mask:0xf bound_ctrl:1
	ds_read_b128 v[66:69], v139 offset:17728
	v_add_f32_dpp v18, v18, v18 row_half_mirror row_mask:0xf bank_mask:0xf bound_ctrl:1
	v_add_f32_dpp v22, v22, v22 row_half_mirror row_mask:0xf bank_mask:0xf bound_ctrl:1
	ds_read_b128 v[62:65], v139 offset:17472
	v_add_f32_dpp v18, v18, v18 row_ror:8 row_mask:0xf bank_mask:0xf bound_ctrl:1
	v_add_f32_dpp v22, v22, v22 row_ror:8 row_mask:0xf bank_mask:0xf bound_ctrl:1
	ds_read_b128 v[70:73], v139 offset:17984
	v_pk_fma_f32 v[0:1], v[114:115], v[18:19], v[4:5] op_sel_hi:[1,0,1] neg_lo:[1,0,0] neg_hi:[1,0,0]
	v_pk_fma_f32 v[2:3], v[116:117], v[18:19], v[6:7] op_sel_hi:[1,0,1] neg_lo:[1,0,0] neg_hi:[1,0,0]
	v_cndmask_b32_e64 v23, v23, v22, s[56:57]
	ds_read_b128 v[78:81], v139 offset:18496
	s_waitcnt lgkmcnt(7)
	v_pk_mul_f32 v[8:9], v[52:53], v[60:61] op_sel_hi:[1,0]
	v_pk_mul_f32 v[10:11], v[54:55], v[60:61] op_sel_hi:[1,0]
	v_pk_mul_f32 v[16:17], v[0:1], v[44:45]
	v_pk_mul_f32 v[20:21], v[0:1], v[122:123]
	ds_read_b128 v[96:99], v139 offset:19584
	v_pk_fma_f32 v[16:17], v[2:3], v[46:47], v[16:17]
	v_pk_fma_f32 v[20:21], v[2:3], v[124:125], v[20:21]
	ds_read_b32 v104, v140 offset:18816
	v_add_f32_e32 v18, v16, v17
	v_add_f32_e32 v22, v20, v21
	v_pk_fma_f32 v[4:5], v[0:1], v[40:41], v[8:9]
	v_add_f32_dpp v18, v18, v18 quad_perm:[1,0,3,2] row_mask:0xf bank_mask:0xf bound_ctrl:1
	v_add_f32_dpp v22, v22, v22 quad_perm:[1,0,3,2] row_mask:0xf bank_mask:0xf bound_ctrl:1
	v_pk_fma_f32 v[6:7], v[2:3], v[42:43], v[10:11]
	v_add_f32_dpp v18, v18, v18 quad_perm:[2,3,0,1] row_mask:0xf bank_mask:0xf bound_ctrl:1
	v_add_f32_dpp v22, v22, v22 quad_perm:[2,3,0,1] row_mask:0xf bank_mask:0xf bound_ctrl:1
	ds_read_b128 v[88:91], v139 offset:19072
	v_add_f32_dpp v18, v18, v18 row_half_mirror row_mask:0xf bank_mask:0xf bound_ctrl:1
	v_add_f32_dpp v22, v22, v22 row_half_mirror row_mask:0xf bank_mask:0xf bound_ctrl:1
	ds_read_b128 v[84:87], v139 offset:18816
	v_add_f32_dpp v18, v18, v18 row_ror:8 row_mask:0xf bank_mask:0xf bound_ctrl:1
	v_add_f32_dpp v22, v22, v22 row_ror:8 row_mask:0xf bank_mask:0xf bound_ctrl:1
	ds_read_b128 v[92:95], v139 offset:19328
	v_pk_fma_f32 v[0:1], v[48:49], v[18:19], v[4:5] op_sel_hi:[1,0,1] neg_lo:[1,0,0] neg_hi:[1,0,0]
	v_pk_fma_f32 v[2:3], v[50:51], v[18:19], v[6:7] op_sel_hi:[1,0,1] neg_lo:[1,0,0] neg_hi:[1,0,0]
	v_cndmask_b32_e64 v23, v23, v22, s[58:59]
	ds_read_b128 v[100:103], v139 offset:19840
	s_waitcnt lgkmcnt(7)
	s_barrier
	s_add_i32 s0, s4, 3
	s_cmp_lt_u32 s0, s5
	s_cbranch_scc0 .Lscan_nold1
	s_mul_i32 s92, s0, s90
	v_add_u32_e32 v132, s92, v28
	v_add_u32_e32 v133, s92, v29
	v_add_u32_e32 v134, s92, v30
	v_add_u32_e32 v135, s92, v31
	v_add_u32_e32 v136, s92, v32
	v_add_u32_e32 v137, s92, v33
	global_load_dwordx4 v[168:171], v132, s[96:97]
	global_load_dwordx4 v[172:175], v133, s[96:97]
	global_load_dwordx4 v[176:179], v134, s[96:97]
	global_load_dwordx4 v[180:183], v135, s[96:97]
	global_load_dwordx4 v[184:187], v136, s[96:97]
	global_load_dword v167, v137, s[96:97]

.LBB0_238:
	v_readlane_b32 s26, v252, 29
	v_readlane_b32 s27, v252, 30
	v_readlane_b32 s36, v252, 33
	v_readlane_b32 s37, v252, 34
	s_lshl_b32 s0, s70, 18
	s_add_u32 s26, s26, s0
	s_addc_u32 s27, s27, 0
	s_add_u32 s36, s36, s0
	s_addc_u32 s37, s37, 0
	s_add_u32 s28, s26, 0x20000
	s_addc_u32 s29, s27, 0
	s_add_u32 s38, s36, 0x20000
	s_addc_u32 s39, s37, 0
	v_lshlrev_b32_e32 v188, 2, v128
	v_mov_b32_e32 v187, 0
	s_movk_i32 s0, 0x0
	v_add_u32_e32 v186, s0, v188
	global_load_dword v146, v186, s[26:27]
	global_load_dword v147, v186, s[28:29]
	global_load_dword v148, v186, s[36:37]
	global_load_dword v149, v186, s[38:39]
	global_load_dword v150, v186, s[26:27] offset:1024
	global_load_dword v151, v186, s[28:29] offset:1024
	global_load_dword v152, v186, s[36:37] offset:1024
	global_load_dword v153, v186, s[38:39] offset:1024
	s_movk_i32 s0, 0x800
	v_add_u32_e32 v186, s0, v188
	global_load_dword v154, v186, s[26:27]
	global_load_dword v155, v186, s[28:29]
	global_load_dword v156, v186, s[36:37]
	global_load_dword v157, v186, s[38:39]
	global_load_dword v158, v186, s[26:27] offset:1024
	global_load_dword v159, v186, s[28:29] offset:1024
	global_load_dword v160, v186, s[36:37] offset:1024
	global_load_dword v161, v186, s[38:39] offset:1024
	s_movk_i32 s0, 0x1000
	v_add_u32_e32 v186, s0, v188
	global_load_dword v162, v186, s[26:27]
	global_load_dword v163, v186, s[28:29]
	global_load_dword v164, v186, s[36:37]
	global_load_dword v165, v186, s[38:39]
	global_load_dword v166, v186, s[26:27] offset:1024
	global_load_dword v167, v186, s[28:29] offset:1024
	global_load_dword v168, v186, s[36:37] offset:1024
	global_load_dword v169, v186, s[38:39] offset:1024
	ds_read_b128 v[72:75], v187 offset:0
	ds_read_b128 v[76:79], v187 offset:16
	ds_read_b128 v[80:83], v187 offset:32
	ds_read_b128 v[84:87], v187 offset:48
	ds_read_b128 v[88:91], v187 offset:64
	ds_read_b128 v[92:95], v187 offset:80
	ds_read_b128 v[96:99], v187 offset:96
	ds_read_b128 v[100:103], v187 offset:112
	s_mov_b32 s1, 0
.Llora_loop:
	s_add_i32 s0, s1, 3
	s_min_u32 s0, s0, 63
	s_lshl_b32 s0, s0, 11
	v_add_u32_e32 v186, s0, v188
	global_load_dword v170, v186, s[26:27]
	global_load_dword v171, v186, s[28:29]
	global_load_dword v172, v186, s[36:37]
	global_load_dword v173, v186, s[38:39]
	global_load_dword v174, v186, s[26:27] offset:1024
	global_load_dword v175, v186, s[28:29] offset:1024
	global_load_dword v176, v186, s[36:37] offset:1024
	global_load_dword v177, v186, s[38:39] offset:1024
	ds_read_b128 v[104:107], v187 offset:128
	ds_read_b128 v[108:111], v187 offset:144
	ds_read_b128 v[112:115], v187 offset:160
	ds_read_b128 v[116:119], v187 offset:176
	ds_read_b128 v[120:123], v187 offset:192
	ds_read_b128 v[132:135], v187 offset:208
	ds_read_b128 v[136:139], v187 offset:224
	ds_read_b128 v[140:143], v187 offset:240
	s_waitcnt vmcnt(24)
	s_waitcnt lgkmcnt(8)
	v_pk_fma_f32 v[66:67], v[146:147], v[72:73], v[66:67] op_sel:[0,0,0] op_sel_hi:[0,1,1]
	v_pk_fma_f32 v[52:53], v[146:147], v[74:75], v[52:53] op_sel:[0,0,0] op_sel_hi:[0,1,1]
	v_pk_fma_f32 v[44:45], v[146:147], v[76:77], v[44:45] op_sel:[0,0,0] op_sel_hi:[0,1,1]
	v_pk_fma_f32 v[36:37], v[146:147], v[78:79], v[36:37] op_sel:[0,0,0] op_sel_hi:[0,1,1]
	v_pk_fma_f32 v[28:29], v[150:151], v[72:73], v[28:29] op_sel:[0,0,0] op_sel_hi:[0,1,1]
	v_pk_fma_f32 v[20:21], v[150:151], v[74:75], v[20:21] op_sel:[0,0,0] op_sel_hi:[0,1,1]
	v_pk_fma_f32 v[12:13], v[150:151], v[76:77], v[12:13] op_sel:[0,0,0] op_sel_hi:[0,1,1]
	v_pk_fma_f32 v[4:5], v[150:151], v[78:79], v[4:5] op_sel:[0,0,0] op_sel_hi:[0,1,1]
	v_pk_fma_f32 v[68:69], v[146:147], v[80:81], v[68:69] op_sel:[1,0,0] op_sel_hi:[1,1,1]
	v_pk_fma_f32 v[54:55], v[146:147], v[82:83], v[54:55] op_sel:[1,0,0] op_sel_hi:[1,1,1]
	v_pk_fma_f32 v[46:47], v[146:147], v[84:85], v[46:47] op_sel:[1,0,0] op_sel_hi:[1,1,1]
	v_pk_fma_f32 v[38:39], v[146:147], v[86:87], v[38:39] op_sel:[1,0,0] op_sel_hi:[1,1,1]
	v_pk_fma_f32 v[30:31], v[150:151], v[80:81], v[30:31] op_sel:[1,0,0] op_sel_hi:[1,1,1]
	v_pk_fma_f32 v[22:23], v[150:151], v[82:83], v[22:23] op_sel:[1,0,0] op_sel_hi:[1,1,1]
	v_pk_fma_f32 v[14:15], v[150:151], v[84:85], v[14:15] op_sel:[1,0,0] op_sel_hi:[1,1,1]
	v_pk_fma_f32 v[6:7], v[150:151], v[86:87], v[6:7] op_sel:[1,0,0] op_sel_hi:[1,1,1]
	v_pk_fma_f32 v[64:65], v[148:149], v[88:89], v[64:65] op_sel:[0,0,0] op_sel_hi:[0,1,1]
	v_pk_fma_f32 v[50:51], v[148:149], v[90:91], v[50:51] op_sel:[0,0,0] op_sel_hi:[0,1,1]
	v_pk_fma_f32 v[42:43], v[148:149], v[92:93], v[42:43] op_sel:[0,0,0] op_sel_hi:[0,1,1]
	v_pk_fma_f32 v[34:35], v[148:149], v[94:95], v[34:35] op_sel:[0,0,0] op_sel_hi:[0,1,1]
	v_pk_fma_f32 v[26:27], v[152:153], v[88:89], v[26:27] op_sel:[0,0,0] op_sel_hi:[0,1,1]
	v_pk_fma_f32 v[18:19], v[152:153], v[90:91], v[18:19] op_sel:[0,0,0] op_sel_hi:[0,1,1]
	v_pk_fma_f32 v[10:11], v[152:153], v[92:93], v[10:11] op_sel:[0,0,0] op_sel_hi:[0,1,1]
	v_pk_fma_f32 v[2:3], v[152:153], v[94:95], v[2:3] op_sel:[0,0,0] op_sel_hi:[0,1,1]
	v_pk_fma_f32 v[70:71], v[148:149], v[96:97], v[70:71] op_sel:[1,0,0] op_sel_hi:[1,1,1]
	v_pk_fma_f32 v[56:57], v[148:149], v[98:99], v[56:57] op_sel:[1,0,0] op_sel_hi:[1,1,1]
	v_pk_fma_f32 v[48:49], v[148:149], v[100:101], v[48:49] op_sel:[1,0,0] op_sel_hi:[1,1,1]
	v_pk_fma_f32 v[40:41], v[148:149], v[102:103], v[40:41] op_sel:[1,0,0] op_sel_hi:[1,1,1]
	v_pk_fma_f32 v[32:33], v[152:153], v[96:97], v[32:33] op_sel:[1,0,0] op_sel_hi:[1,1,1]
	v_pk_fma_f32 v[24:25], v[152:153], v[98:99], v[24:25] op_sel:[1,0,0] op_sel_hi:[1,1,1]
	v_pk_fma_f32 v[16:17], v[152:153], v[100:101], v[16:17] op_sel:[1,0,0] op_sel_hi:[1,1,1]
	v_pk_fma_f32 v[8:9], v[152:153], v[102:103], v[8:9] op_sel:[1,0,0] op_sel_hi:[1,1,1]
	s_add_i32 s0, s1, 4
	s_min_u32 s0, s0, 63
	s_lshl_b32 s0, s0, 11
	v_add_u32_e32 v186, s0, v188
	global_load_dword v146, v186, s[26:27]
	global_load_dword v147, v186, s[28:29]
	global_load_dword v148, v186, s[36:37]
	global_load_dword v149, v186, s[38:39]
	global_load_dword v150, v186, s[26:27] offset:1024
	global_load_dword v151, v186, s[28:29] offset:1024
	global_load_dword v152, v186, s[36:37] offset:1024
	global_load_dword v153, v186, s[38:39] offset:1024
	ds_read_b128 v[72:75], v187 offset:256
	ds_read_b128 v[76:79], v187 offset:272
	ds_read_b128 v[80:83], v187 offset:288
	ds_read_b128 v[84:87], v187 offset:304
	ds_read_b128 v[88:91], v187 offset:320
	ds_read_b128 v[92:95], v187 offset:336
	ds_read_b128 v[96:99], v187 offset:352
	ds_read_b128 v[100:103], v187 offset:368
	s_waitcnt vmcnt(24)
	s_waitcnt lgkmcnt(8)
	v_pk_fma_f32 v[66:67], v[154:155], v[104:105], v[66:67] op_sel:[0,0,0] op_sel_hi:[0,1,1]
	v_pk_fma_f32 v[52:53], v[154:155], v[106:107], v[52:53] op_sel:[0,0,0] op_sel_hi:[0,1,1]
	v_pk_fma_f32 v[44:45], v[154:155], v[108:109], v[44:45] op_sel:[0,0,0] op_sel_hi:[0,1,1]
	v_pk_fma_f32 v[36:37], v[154:155], v[110:111], v[36:37] op_sel:[0,0,0] op_sel_hi:[0,1,1]
	v_pk_fma_f32 v[28:29], v[158:159], v[104:105], v[28:29] op_sel:[0,0,0] op_sel_hi:[0,1,1]
	v_pk_fma_f32 v[20:21], v[158:159], v[106:107], v[20:21] op_sel:[0,0,0] op_sel_hi:[0,1,1]
	v_pk_fma_f32 v[12:13], v[158:159], v[108:109], v[12:13] op_sel:[0,0,0] op_sel_hi:[0,1,1]
	v_pk_fma_f32 v[4:5], v[158:159], v[110:111], v[4:5] op_sel:[0,0,0] op_sel_hi:[0,1,1]
	v_pk_fma_f32 v[68:69], v[154:155], v[112:113], v[68:69] op_sel:[1,0,0] op_sel_hi:[1,1,1]
	v_pk_fma_f32 v[54:55], v[154:155], v[114:115], v[54:55] op_sel:[1,0,0] op_sel_hi:[1,1,1]
	v_pk_fma_f32 v[46:47], v[154:155], v[116:117], v[46:47] op_sel:[1,0,0] op_sel_hi:[1,1,1]
	v_pk_fma_f32 v[38:39], v[154:155], v[118:119], v[38:39] op_sel:[1,0,0] op_sel_hi:[1,1,1]
	v_pk_fma_f32 v[30:31], v[158:159], v[112:113], v[30:31] op_sel:[1,0,0] op_sel_hi:[1,1,1]
	v_pk_fma_f32 v[22:23], v[158:159], v[114:115], v[22:23] op_sel:[1,0,0] op_sel_hi:[1,1,1]
	v_pk_fma_f32 v[14:15], v[158:159], v[116:117], v[14:15] op_sel:[1,0,0] op_sel_hi:[1,1,1]
	v_pk_fma_f32 v[6:7], v[158:159], v[118:119], v[6:7] op_sel:[1,0,0] op_sel_hi:[1,1,1]
	v_pk_fma_f32 v[64:65], v[156:157], v[120:121], v[64:65] op_sel:[0,0,0] op_sel_hi:[0,1,1]
	v_pk_fma_f32 v[50:51], v[156:157], v[122:123], v[50:51] op_sel:[0,0,0] op_sel_hi:[0,1,1]
	v_pk_fma_f32 v[42:43], v[156:157], v[132:133], v[42:43] op_sel:[0,0,0] op_sel_hi:[0,1,1]
	v_pk_fma_f32 v[34:35], v[156:157], v[134:135], v[34:35] op_sel:[0,0,0] op_sel_hi:[0,1,1]
	v_pk_fma_f32 v[26:27], v[160:161], v[120:121], v[26:27] op_sel:[0,0,0] op_sel_hi:[0,1,1]
	v_pk_fma_f32 v[18:19], v[160:161], v[122:123], v[18:19] op_sel:[0,0,0] op_sel_hi:[0,1,1]
	v_pk_fma_f32 v[10:11], v[160:161], v[132:133], v[10:11] op_sel:[0,0,0] op_sel_hi:[0,1,1]
	v_pk_fma_f32 v[2:3], v[160:161], v[134:135], v[2:3] op_sel:[0,0,0] op_sel_hi:[0,1,1]
	v_pk_fma_f32 v[70:71], v[156:157], v[136:137], v[70:71] op_sel:[1,0,0] op_sel_hi:[1,1,1]
	v_pk_fma_f32 v[56:57], v[156:157], v[138:139], v[56:57] op_sel:[1,0,0] op_sel_hi:[1,1,1]
	v_pk_fma_f32 v[48:49], v[156:157], v[140:141], v[48:49] op_sel:[1,0,0] op_sel_hi:[1,1,1]
	v_pk_fma_f32 v[40:41], v[156:157], v[142:143], v[40:41] op_sel:[1,0,0] op_sel_hi:[1,1,1]
	v_pk_fma_f32 v[32:33], v[160:161], v[136:137], v[32:33] op_sel:[1,0,0] op_sel_hi:[1,1,1]
	v_pk_fma_f32 v[24:25], v[160:161], v[138:139], v[24:25] op_sel:[1,0,0] op_sel_hi:[1,1,1]
	v_pk_fma_f32 v[16:17], v[160:161], v[140:141], v[16:17] op_sel:[1,0,0] op_sel_hi:[1,1,1]
	v_pk_fma_f32 v[8:9], v[160:161], v[142:143], v[8:9] op_sel:[1,0,0] op_sel_hi:[1,1,1]
	s_add_i32 s0, s1, 5
	s_min_u32 s0, s0, 63
	s_lshl_b32 s0, s0, 11
	v_add_u32_e32 v186, s0, v188
	global_load_dword v154, v186, s[26:27]
	global_load_dword v155, v186, s[28:29]
	global_load_dword v156, v186, s[36:37]
	global_load_dword v157, v186, s[38:39]
	global_load_dword v158, v186, s[26:27] offset:1024
	global_load_dword v159, v186, s[28:29] offset:1024
	global_load_dword v160, v186, s[36:37] offset:1024
	global_load_dword v161, v186, s[38:39] offset:1024
	ds_read_b128 v[104:107], v187 offset:384
	ds_read_b128 v[108:111], v187 offset:400
	ds_read_b128 v[112:115], v187 offset:416
	ds_read_b128 v[116:119], v187 offset:432
	ds_read_b128 v[120:123], v187 offset:448
	ds_read_b128 v[132:135], v187 offset:464
	ds_read_b128 v[136:139], v187 offset:480
	ds_read_b128 v[140:143], v187 offset:496
	s_waitcnt vmcnt(24)
	s_waitcnt lgkmcnt(8)
	v_pk_fma_f32 v[66:67], v[162:163], v[72:73], v[66:67] op_sel:[0,0,0] op_sel_hi:[0,1,1]
	v_pk_fma_f32 v[52:53], v[162:163], v[74:75], v[52:53] op_sel:[0,0,0] op_sel_hi:[0,1,1]
	v_pk_fma_f32 v[44:45], v[162:163], v[76:77], v[44:45] op_sel:[0,0,0] op_sel_hi:[0,1,1]
	v_pk_fma_f32 v[36:37], v[162:163], v[78:79], v[36:37] op_sel:[0,0,0] op_sel_hi:[0,1,1]
	v_pk_fma_f32 v[28:29], v[166:167], v[72:73], v[28:29] op_sel:[0,0,0] op_sel_hi:[0,1,1]
	v_pk_fma_f32 v[20:21], v[166:167], v[74:75], v[20:21] op_sel:[0,0,0] op_sel_hi:[0,1,1]
	v_pk_fma_f32 v[12:13], v[166:167], v[76:77], v[12:13] op_sel:[0,0,0] op_sel_hi:[0,1,1]
	v_pk_fma_f32 v[4:5], v[166:167], v[78:79], v[4:5] op_sel:[0,0,0] op_sel_hi:[0,1,1]
	v_pk_fma_f32 v[68:69], v[162:163], v[80:81], v[68:69] op_sel:[1,0,0] op_sel_hi:[1,1,1]
	v_pk_fma_f32 v[54:55], v[162:163], v[82:83], v[54:55] op_sel:[1,0,0] op_sel_hi:[1,1,1]
	v_pk_fma_f32 v[46:47], v[162:163], v[84:85], v[46:47] op_sel:[1,0,0] op_sel_hi:[1,1,1]
	v_pk_fma_f32 v[38:39], v[162:163], v[86:87], v[38:39] op_sel:[1,0,0] op_sel_hi:[1,1,1]
	v_pk_fma_f32 v[30:31], v[166:167], v[80:81], v[30:31] op_sel:[1,0,0] op_sel_hi:[1,1,1]
	v_pk_fma_f32 v[22:23], v[166:167], v[82:83], v[22:23] op_sel:[1,0,0] op_sel_hi:[1,1,1]
	v_pk_fma_f32 v[14:15], v[166:167], v[84:85], v[14:15] op_sel:[1,0,0] op_sel_hi:[1,1,1]
	v_pk_fma_f32 v[6:7], v[166:167], v[86:87], v[6:7] op_sel:[1,0,0] op_sel_hi:[1,1,1]
	v_pk_fma_f32 v[64:65], v[164:165], v[88:89], v[64:65] op_sel:[0,0,0] op_sel_hi:[0,1,1]
	v_pk_fma_f32 v[50:51], v[164:165], v[90:91], v[50:51] op_sel:[0,0,0] op_sel_hi:[0,1,1]
	v_pk_fma_f32 v[42:43], v[164:165], v[92:93], v[42:43] op_sel:[0,0,0] op_sel_hi:[0,1,1]
	v_pk_fma_f32 v[34:35], v[164:165], v[94:95], v[34:35] op_sel:[0,0,0] op_sel_hi:[0,1,1]
	v_pk_fma_f32 v[26:27], v[168:169], v[88:89], v[26:27] op_sel:[0,0,0] op_sel_hi:[0,1,1]
	v_pk_fma_f32 v[18:19], v[168:169], v[90:91], v[18:19] op_sel:[0,0,0] op_sel_hi:[0,1,1]
	v_pk_fma_f32 v[10:11], v[168:169], v[92:93], v[10:11] op_sel:[0,0,0] op_sel_hi:[0,1,1]
	v_pk_fma_f32 v[2:3], v[168:169], v[94:95], v[2:3] op_sel:[0,0,0] op_sel_hi:[0,1,1]
	v_pk_fma_f32 v[70:71], v[164:165], v[96:97], v[70:71] op_sel:[1,0,0] op_sel_hi:[1,1,1]
	v_pk_fma_f32 v[56:57], v[164:165], v[98:99], v[56:57] op_sel:[1,0,0] op_sel_hi:[1,1,1]
	v_pk_fma_f32 v[48:49], v[164:165], v[100:101], v[48:49] op_sel:[1,0,0] op_sel_hi:[1,1,1]
	v_pk_fma_f32 v[40:41], v[164:165], v[102:103], v[40:41] op_sel:[1,0,0] op_sel_hi:[1,1,1]
	v_pk_fma_f32 v[32:33], v[168:169], v[96:97], v[32:33] op_sel:[1,0,0] op_sel_hi:[1,1,1]
	v_pk_fma_f32 v[24:25], v[168:169], v[98:99], v[24:25] op_sel:[1,0,0] op_sel_hi:[1,1,1]
	v_pk_fma_f32 v[16:17], v[168:169], v[100:101], v[16:17] op_sel:[1,0,0] op_sel_hi:[1,1,1]
	v_pk_fma_f32 v[8:9], v[168:169], v[102:103], v[8:9] op_sel:[1,0,0] op_sel_hi:[1,1,1]
	s_add_i32 s0, s1, 6
	s_min_u32 s0, s0, 63
	s_lshl_b32 s0, s0, 11
	v_add_u32_e32 v186, s0, v188
	global_load_dword v162, v186, s[26:27]
	global_load_dword v163, v186, s[28:29]
	global_load_dword v164, v186, s[36:37]
	global_load_dword v165, v186, s[38:39]
	global_load_dword v166, v186, s[26:27] offset:1024
	global_load_dword v167, v186, s[28:29] offset:1024
	global_load_dword v168, v186, s[36:37] offset:1024
	global_load_dword v169, v186, s[38:39] offset:1024
	ds_read_b128 v[72:75], v187 offset:512
	ds_read_b128 v[76:79], v187 offset:528
	ds_read_b128 v[80:83], v187 offset:544
	ds_read_b128 v[84:87], v187 offset:560
	ds_read_b128 v[88:91], v187 offset:576
	ds_read_b128 v[92:95], v187 offset:592
	ds_read_b128 v[96:99], v187 offset:608
	ds_read_b128 v[100:103], v187 offset:624
	s_waitcnt vmcnt(24)
	s_waitcnt lgkmcnt(8)
	v_pk_fma_f32 v[66:67], v[170:171], v[104:105], v[66:67] op_sel:[0,0,0] op_sel_hi:[0,1,1]
	v_pk_fma_f32 v[52:53], v[170:171], v[106:107], v[52:53] op_sel:[0,0,0] op_sel_hi:[0,1,1]
	v_pk_fma_f32 v[44:45], v[170:171], v[108:109], v[44:45] op_sel:[0,0,0] op_sel_hi:[0,1,1]
	v_pk_fma_f32 v[36:37], v[170:171], v[110:111], v[36:37] op_sel:[0,0,0] op_sel_hi:[0,1,1]
	v_pk_fma_f32 v[28:29], v[174:175], v[104:105], v[28:29] op_sel:[0,0,0] op_sel_hi:[0,1,1]
	v_pk_fma_f32 v[20:21], v[174:175], v[106:107], v[20:21] op_sel:[0,0,0] op_sel_hi:[0,1,1]
	v_pk_fma_f32 v[12:13], v[174:175], v[108:109], v[12:13] op_sel:[0,0,0] op_sel_hi:[0,1,1]
	v_pk_fma_f32 v[4:5], v[174:175], v[110:111], v[4:5] op_sel:[0,0,0] op_sel_hi:[0,1,1]
	v_pk_fma_f32 v[68:69], v[170:171], v[112:113], v[68:69] op_sel:[1,0,0] op_sel_hi:[1,1,1]
	v_pk_fma_f32 v[54:55], v[170:171], v[114:115], v[54:55] op_sel:[1,0,0] op_sel_hi:[1,1,1]
	v_pk_fma_f32 v[46:47], v[170:171], v[116:117], v[46:47] op_sel:[1,0,0] op_sel_hi:[1,1,1]
	v_pk_fma_f32 v[38:39], v[170:171], v[118:119], v[38:39] op_sel:[1,0,0] op_sel_hi:[1,1,1]
	v_pk_fma_f32 v[30:31], v[174:175], v[112:113], v[30:31] op_sel:[1,0,0] op_sel_hi:[1,1,1]
	v_pk_fma_f32 v[22:23], v[174:175], v[114:115], v[22:23] op_sel:[1,0,0] op_sel_hi:[1,1,1]
	v_pk_fma_f32 v[14:15], v[174:175], v[116:117], v[14:15] op_sel:[1,0,0] op_sel_hi:[1,1,1]
	v_pk_fma_f32 v[6:7], v[174:175], v[118:119], v[6:7] op_sel:[1,0,0] op_sel_hi:[1,1,1]
	v_pk_fma_f32 v[64:65], v[172:173], v[120:121], v[64:65] op_sel:[0,0,0] op_sel_hi:[0,1,1]
	v_pk_fma_f32 v[50:51], v[172:173], v[122:123], v[50:51] op_sel:[0,0,0] op_sel_hi:[0,1,1]
	v_pk_fma_f32 v[42:43], v[172:173], v[132:133], v[42:43] op_sel:[0,0,0] op_sel_hi:[0,1,1]
	v_pk_fma_f32 v[34:35], v[172:173], v[134:135], v[34:35] op_sel:[0,0,0] op_sel_hi:[0,1,1]
	v_pk_fma_f32 v[26:27], v[176:177], v[120:121], v[26:27] op_sel:[0,0,0] op_sel_hi:[0,1,1]
	v_pk_fma_f32 v[18:19], v[176:177], v[122:123], v[18:19] op_sel:[0,0,0] op_sel_hi:[0,1,1]
	v_pk_fma_f32 v[10:11], v[176:177], v[132:133], v[10:11] op_sel:[0,0,0] op_sel_hi:[0,1,1]
	v_pk_fma_f32 v[2:3], v[176:177], v[134:135], v[2:3] op_sel:[0,0,0] op_sel_hi:[0,1,1]
	v_pk_fma_f32 v[70:71], v[172:173], v[136:137], v[70:71] op_sel:[1,0,0] op_sel_hi:[1,1,1]
	v_pk_fma_f32 v[56:57], v[172:173], v[138:139], v[56:57] op_sel:[1,0,0] op_sel_hi:[1,1,1]
	v_pk_fma_f32 v[48:49], v[172:173], v[140:141], v[48:49] op_sel:[1,0,0] op_sel_hi:[1,1,1]
	v_pk_fma_f32 v[40:41], v[172:173], v[142:143], v[40:41] op_sel:[1,0,0] op_sel_hi:[1,1,1]
	v_pk_fma_f32 v[32:33], v[176:177], v[136:137], v[32:33] op_sel:[1,0,0] op_sel_hi:[1,1,1]
	v_pk_fma_f32 v[24:25], v[176:177], v[138:139], v[24:25] op_sel:[1,0,0] op_sel_hi:[1,1,1]
	v_pk_fma_f32 v[16:17], v[176:177], v[140:141], v[16:17] op_sel:[1,0,0] op_sel_hi:[1,1,1]
	v_pk_fma_f32 v[8:9], v[176:177], v[142:143], v[8:9] op_sel:[1,0,0] op_sel_hi:[1,1,1]
	v_add_u32_e32 v187, 0x200, v187
	s_add_i32 s1, s1, 4
	s_cmp_lt_u32 s1, 64
	s_cbranch_scc1 .Llora_loop
	s_waitcnt vmcnt(0) lgkmcnt(0)
	s_cmpk_lt_i32 s25, 0x200
	s_movk_i32 s0, 0x7f8
	s_cselect_b32 s0, 0xf8, s0
	v_lshl_add_u64 v[58:59], v[0:1], 2, s[46:47]
	s_and_b32 s0, s0, s60
	s_mul_i32 s26, s60, 0x4a00
	v_readlane_b32 s2, v254, 63
	v_add_co_u32_e32 v62, vcc, 0x1000, v58
	s_mul_hi_i32 s1, s60, 0x4a00
	v_readlane_b32 s3, v255, 0
	s_add_u32 s40, s2, s26
	v_lshl_add_u64 v[60:61], v[0:1], 1, v[232:233]
	v_addc_co_u32_e32 v63, vcc, 0, v59, vcc
	s_addc_u32 s41, s3, s1
	global_load_dword v75, v[58:59], off
	global_load_dword v76, v[58:59], off offset:2048
	global_load_dword v74, v[62:63], off
	v_lshl_add_u64 v[62:63], s[40:41], 0, v[60:61]
	global_load_ushort v80, v[62:63], off
	s_cmp_lg_u32 s0, 0
	s_cselect_b64 s[0:1], -1, 0
	v_lshl_add_u64 v[60:61], s[2:3], 0, v[60:61]
	v_mov_b32_e32 v77, 0
	s_and_b64 vcc, exec, s[0:1]
	v_mov_b32_e32 v87, 0
	s_cbranch_vccz .LBB0_241
	s_add_i32 s26, s60, -1
	v_mad_i64_i32 v[62:63], s[26:27], s26, v214, v[60:61]
	global_load_ushort v62, v[62:63], off
	s_waitcnt vmcnt(0)
	v_lshlrev_b32_e32 v87, 16, v62

	.amdhsa_kernel _Z14fwd_megakernel6Paramsii
		.amdhsa_group_segment_fixed_size 77824
		.amdhsa_private_segment_fixed_size 0
		.amdhsa_kernarg_size 592
		.amdhsa_user_sgpr_count 2
		.amdhsa_user_sgpr_dispatch_ptr 0
		.amdhsa_user_sgpr_queue_ptr 0
		.amdhsa_user_sgpr_kernarg_segment_ptr 1
		.amdhsa_user_sgpr_dispatch_id 0
		.amdhsa_user_sgpr_kernarg_preload_length 0
		.amdhsa_user_sgpr_kernarg_preload_offset 0
		.amdhsa_user_sgpr_private_segment_size 0
		.amdhsa_uses_dynamic_stack 0
		.amdhsa_enable_private_segment 0
		.amdhsa_system_sgpr_workgroup_id_x 1
		.amdhsa_system_sgpr_workgroup_id_y 0
		.amdhsa_system_sgpr_workgroup_id_z 0
		.amdhsa_system_sgpr_workgroup_info 0
		.amdhsa_system_vgpr_workitem_id 2
		.amdhsa_next_free_vgpr 256
		.amdhsa_next_free_sgpr 102
		.amdhsa_accum_offset 256
		.amdhsa_reserve_vcc 1
		.amdhsa_float_round_mode_32 0
		.amdhsa_float_round_mode_16_64 0
		.amdhsa_float_denorm_mode_32 3
		.amdhsa_float_denorm_mode_16_64 3
		.amdhsa_dx10_clamp 1
		.amdhsa_ieee_mode 1
		.amdhsa_fp16_overflow 0
		.amdhsa_tg_split 0
		.amdhsa_exception_fp_ieee_invalid_op 0
		.amdhsa_exception_fp_denorm_src 0
		.amdhsa_exception_fp_ieee_div_zero 0
		.amdhsa_exception_fp_ieee_overflow 0
		.amdhsa_exception_fp_ieee_underflow 0
		.amdhsa_exception_fp_ieee_inexact 0
		.amdhsa_exception_int_div_zero 0
	.end_amdhsa_kernel

amdhsa.kernels:
  - .agpr_count:     0
    .args:
      - .offset:         0
        .size:           328
        .value_kind:     by_value
      - .offset:         328
        .size:           4
        .value_kind:     by_value
      - .offset:         332
        .size:           4
        .value_kind:     by_value
      - .offset:         336
        .size:           4
        .value_kind:     hidden_block_count_x
      - .offset:         340
        .size:           4
        .value_kind:     hidden_block_count_y
      - .offset:         344
        .size:           4
        .value_kind:     hidden_block_count_z
      - .offset:         348
        .size:           2
        .value_kind:     hidden_group_size_x
      - .offset:         350
        .size:           2
        .value_kind:     hidden_group_size_y
      - .offset:         352
        .size:           2
        .value_kind:     hidden_group_size_z
      - .offset:         354
        .size:           2
        .value_kind:     hidden_remainder_x
      - .offset:         356
        .size:           2
        .value_kind:     hidden_remainder_y
      - .offset:         358
        .size:           2
        .value_kind:     hidden_remainder_z
      - .offset:         376
        .size:           8
        .value_kind:     hidden_global_offset_x
      - .offset:         384
        .size:           8
        .value_kind:     hidden_global_offset_y
      - .offset:         392
        .size:           8
        .value_kind:     hidden_global_offset_z
      - .offset:         400
        .size:           2
        .value_kind:     hidden_grid_dims
      - .offset:         424
        .size:           8
        .value_kind:     hidden_multigrid_sync_arg
    .group_segment_fixed_size: 77824
    .kernarg_segment_align: 8
    .kernarg_segment_size: 592
    .language:       OpenCL C
    .language_version:
      - 2
      - 0
    .max_flat_workgroup_size: 256
    .name:           _Z14fwd_megakernel6Paramsii
    .private_segment_fixed_size: 0
    .sgpr_count:     108
    .sgpr_spill_count: 253
    .symbol:         _Z14fwd_megakernel6Paramsii.kd
    .uniform_work_group_size: 1
    .uses_dynamic_stack: false
    .vgpr_count:     256
    .vgpr_spill_count: 0
    .wavefront_size: 64
